# v33: v28 + first GU epilogue row-scale LDS read issued before the half-alignment barrier
# baseline (speedup 1.0000x reference)
; #define PG8_STAGE(bufoff, gbase, voff) do { _Pragma("unroll") for (int _i = 0; _i < 2; ++_i) \
;         __builtin_amdgcn_global_load_lds((const unsigned*)((const char*)(gbase) + (voff)[_i]), (PG8_LAS unsigned*)(lds + (bufoff) + ldsw + _i * 8192), 16, 0, 0); } while (0)
; #define PG8_LDA(dst, b, h) do { _Pragma("unroll") for (int m = 0; m < 4; ++m) _Pragma("unroll") for (int k = 0; k < 2; ++k) dst[m][k] = *(const PG8_LAS bf16x8*)(lds + PG8_SA(b, h) + aoff + m * 2048 + k * 1024); } while (0)
; #define PG8_LDB(dst, b, h) do { _Pragma("unroll") for (int n = 0; n < 2; ++n) _Pragma("unroll") for (int k = 0; k < 2; ++k) dst[n][k] = *(const PG8_LAS bf16x8*)(lds + PG8_SB(b, h) + boff + n * 2048 + k * 1024); } while (0)
; #define PG8_MMA(ai, bj, At, Bt) do { __builtin_amdgcn_s_setprio(1); _Pragma("unroll") for (int m = 0; m < 4; ++m) _Pragma("unroll") for (int n = 0; n < 2; ++n) _Pragma("unroll") for (int k = 0; k < 2; ++k) \
;         acc[ai][bj][m][n] = __builtin_amdgcn_mfma_f32_16x16x32_bf16(Bt[n][k], At[m][k], acc[ai][bj][m][n], 0, 0, 0); __builtin_amdgcn_s_setprio(0); } while (0)
; #define PG8_WAIT_V(n) asm volatile("s_waitcnt vmcnt(" #n ")" ::: "memory")
; template <class Epi, class Sched, bool ALIGN_EPI = false, bool SP2 = false>
; __device__ __forceinline__ void gemm_phase(PG8_LAS unsigned char* lds, const Gemm g, const Sched& S, const Epi& E) {
;     ...
;             PG8_LDB(B0, 0, 0); PG8_LDB(B1, 0, 1); PG8_SCHED; PG8_LDA(At, 0, 0); PG8_STAGE(PG8_SA(1, 1), a1 + hstep, voffA);
;             PG8_WAIT_V(8); PG8_WAIT_L(0); PG8_BAR; PG8_MMA(0, 0, At, B0); PG8_MMA(0, 1, At, B1); PG8_BAR; PG8_SCHED;
;             PG8_LDA(At, 0, 1); PG8_STAGE(PG8_SB(0, 0), b2, voffB); PG8_STAGE(PG8_SB(0, 1), b2 + hstep, voffB); PG8_STAGE(PG8_SA(0, 0), a2, voffA);
;             PG8_WAIT_V(8); PG8_WAIT_L(0); PG8_BAR; PG8_MMA(1, 0, At, B0); PG8_MMA(1, 1, At, B1); PG8_BAR; PG8_SCHED;
;             PG8_LDB(B0, 1, 0); PG8_LDB(B1, 1, 1); PG8_SCHED; PG8_LDA(At, 1, 0); PG8_STAGE(PG8_SA(0, 1), a2 + hstep, voffA);
;             PG8_WAIT_V(8); PG8_WAIT_L(0); PG8_BAR; PG8_MMA(0, 0, At, B0); PG8_MMA(0, 1, At, B1); PG8_BAR; PG8_SCHED;
;             PG8_LDA(At, 1, 1); PG8_STAGE(PG8_SB(1, 0), b3, voffB); PG8_STAGE(PG8_SB(1, 1), b3 + hstep, voffB); PG8_STAGE(PG8_SA(1, 0), a3, voffA);
;             PG8_WAIT_V(8); PG8_WAIT_L(0); PG8_BAR; PG8_MMA(1, 0, At, B0); PG8_MMA(1, 1, At, B1); PG8_BAR; PG8_SCHED;
.Lrs_gu_b:
	v_add_u32_e32 v156, s52, v141
	v_add_u32_e32 v172, s53, v141
	ds_read_b128 v[144:147], v156
	ds_read_b128 v[148:151], v156 offset:1024
	ds_read_b128 v[152:155], v156 offset:2048
	ds_read_b128 v[156:159], v156 offset:3072
	ds_read_b128 v[160:163], v172
	ds_read_b128 v[164:167], v172 offset:1024
	ds_read_b128 v[168:171], v172 offset:2048
	ds_read_b128 v[172:175], v172 offset:3072
	s_add_u32 s26, s26, 0x40000
	s_addc_u32 s27, s27, 0
	s_mov_b32 m0, s42
	v_lshl_add_u64 v[234:235], s[26:27], 0, v[134:135]
	ds_read_b128 v[176:179], v143 offset:32768
	ds_read_b128 v[180:183], v143 offset:33792
	ds_read_b128 v[194:197], v143 offset:34816
	ds_read_b128 v[198:201], v143 offset:35840
	ds_read_b128 v[202:205], v143 offset:36864
	ds_read_b128 v[206:209], v143 offset:37888
	ds_read_b128 v[210:213], v143 offset:38912
	ds_read_b128 v[228:231], v143 offset:39936
	global_load_lds_dwordx4 v[234:235], off
	v_lshl_add_u64 v[234:235], s[26:27], 0, v[130:131]
	s_mov_b32 m0, s43
	s_nop 0
	global_load_lds_dwordx4 v[234:235], off
	s_waitcnt vmcnt(8)
	s_waitcnt lgkmcnt(0)
	s_barrier
	s_setprio 1
	s_waitcnt lgkmcnt(0)
	v_mfma_f32_16x16x32_bf16 v[124:127], v[144:147], v[176:179], v[124:127]
	v_mfma_f32_16x16x32_bf16 v[116:119], v[152:155], v[176:179], v[116:119]
	v_mfma_f32_16x16x32_bf16 v[108:111], v[144:147], v[194:197], v[108:111]
	v_mfma_f32_16x16x32_bf16 v[100:103], v[152:155], v[194:197], v[100:103]
	v_mfma_f32_16x16x32_bf16 v[92:95], v[144:147], v[202:205], v[92:95]
	v_mfma_f32_16x16x32_bf16 v[84:87], v[152:155], v[202:205], v[84:87]
	v_mfma_f32_16x16x32_bf16 v[76:79], v[144:147], v[210:213], v[76:79]
	v_mfma_f32_16x16x32_bf16 v[68:71], v[152:155], v[210:213], v[68:71]
	v_mfma_f32_16x16x32_bf16 v[124:127], v[148:151], v[180:183], v[124:127]
	v_mfma_f32_16x16x32_bf16 v[116:119], v[156:159], v[180:183], v[116:119]
	v_mfma_f32_16x16x32_bf16 v[108:111], v[148:151], v[198:201], v[108:111]
	v_mfma_f32_16x16x32_bf16 v[100:103], v[156:159], v[198:201], v[100:103]
	v_mfma_f32_16x16x32_bf16 v[92:95], v[148:151], v[206:209], v[92:95]
	v_mfma_f32_16x16x32_bf16 v[84:87], v[156:159], v[206:209], v[84:87]
	v_mfma_f32_16x16x32_bf16 v[76:79], v[148:151], v[228:231], v[76:79]
	v_mfma_f32_16x16x32_bf16 v[68:71], v[156:159], v[228:231], v[68:71]
	s_setprio 0
	s_setprio 1
	v_mfma_f32_16x16x32_bf16 v[120:123], v[160:163], v[176:179], v[120:123]
	v_mfma_f32_16x16x32_bf16 v[112:115], v[168:171], v[176:179], v[112:115]
	v_mfma_f32_16x16x32_bf16 v[104:107], v[160:163], v[194:197], v[104:107]
	v_mfma_f32_16x16x32_bf16 v[96:99], v[168:171], v[194:197], v[96:99]
	v_mfma_f32_16x16x32_bf16 v[88:91], v[160:163], v[202:205], v[88:91]
	v_mfma_f32_16x16x32_bf16 v[80:83], v[168:171], v[202:205], v[80:83]
	v_mfma_f32_16x16x32_bf16 v[72:75], v[160:163], v[210:213], v[72:75]
	v_mfma_f32_16x16x32_bf16 v[64:67], v[168:171], v[210:213], v[64:67]
	v_mfma_f32_16x16x32_bf16 v[120:123], v[164:167], v[180:183], v[120:123]
	v_mfma_f32_16x16x32_bf16 v[112:115], v[172:175], v[180:183], v[112:115]
	v_mfma_f32_16x16x32_bf16 v[104:107], v[164:167], v[198:201], v[104:107]
	v_mfma_f32_16x16x32_bf16 v[96:99], v[172:175], v[198:201], v[96:99]
	v_mfma_f32_16x16x32_bf16 v[88:91], v[164:167], v[206:209], v[88:91]
	v_mfma_f32_16x16x32_bf16 v[80:83], v[172:175], v[206:209], v[80:83]
	v_mfma_f32_16x16x32_bf16 v[72:75], v[164:167], v[228:231], v[72:75]
	v_mfma_f32_16x16x32_bf16 v[64:67], v[172:175], v[228:231], v[64:67]
	s_setprio 0
	s_barrier
	s_add_i32 s26, s52, s39
	v_lshl_add_u64 v[214:215], v[214:215], 0, s[96:97]
	s_mov_b32 m0, s26
	ds_read_b128 v[176:179], v143 offset:49152
	ds_read_b128 v[180:183], v143 offset:50176
	ds_read_b128 v[194:197], v143 offset:51200
	ds_read_b128 v[198:201], v143 offset:52224
	ds_read_b128 v[202:205], v143 offset:53248
	ds_read_b128 v[206:209], v143 offset:54272
	ds_read_b128 v[210:213], v143 offset:55296
	ds_read_b128 v[228:231], v143 offset:56320
	global_load_lds_dwordx4 v[214:215], off
	s_add_i32 m0, s26, 0x2000
	s_add_u32 s24, s24, 0x40080
	v_lshl_add_u64 v[214:215], v[224:225], 0, s[96:97]
	s_addc_u32 s25, s25, 0
	s_add_i32 s26, s53, s39
	global_load_lds_dwordx4 v[214:215], off
	v_lshl_add_u64 v[214:215], s[24:25], 0, v[132:133]
	s_mov_b32 m0, s26
	s_nop 0
	global_load_lds_dwordx4 v[214:215], off
	v_lshl_add_u64 v[214:215], s[24:25], 0, v[128:129]
	s_add_i32 m0, s26, 0x2000
	s_nop 0
	global_load_lds_dwordx4 v[214:215], off
	v_lshl_add_u64 v[214:215], v[226:227], 0, s[96:97]
	s_mov_b32 m0, s44
	s_nop 0
	global_load_lds_dwordx4 v[214:215], off
	v_lshl_add_u64 v[214:215], v[232:233], 0, s[96:97]
	s_mov_b32 m0, s45
	s_nop 0
	global_load_lds_dwordx4 v[214:215], off
	s_waitcnt vmcnt(8)
	s_waitcnt lgkmcnt(0)
	s_barrier
;     __device__ __forceinline__ void operator()(const f32x4 (&acc)[2][2][4][2], const Unit& u, int wr, int wc, int fr, int fq) const {
;         PG8_LAS const float* R = stage_rstd((const float*)(ws + WS_PS), lds, u.pm);
; #pragma unroll
;         for (int ai = 0; ai < 2; ++ai)
; #pragma unroll
;             for (int m = 0; m < 4; ++m) {
;                 const int row = u.pm * BM + ai * HALF + wr * 64 + m * 16 + fr;
;                 const float rs = R[ai * HALF + wr * 64 + m * 16 + fr];
;                 bf16_t* ACT = (bf16_t*)(ws + WS_ACT);
;                 f32x4 a[2];
; #pragma unroll
;                 for (int n = 0; n < 2; ++n) {
;                     const f32x4 g = acc[ai][0][m][n] * rs, uu = acc[ai][1][m][n] * rs;
; #pragma unroll
;                     for (int j = 0; j < 4; ++j) a[n][j] = g[j] * __builtin_amdgcn_rcpf(1.0f + __builtin_amdgcn_exp2f(-1.4426950408889634f * g[j])) * uu[j];
;                 }
;                 *(u32x4*)(ACT + (size_t)row * 2816 + u.pn * 128 + wc * 32 + 8 * fq) = pack8(a[0], a[1]);
;             }
; template <class Epi, class Sched, bool ALIGN_EPI = false, bool SP2 = false>
; __device__ __forceinline__ void gemm_phase(PG8_LAS unsigned char* lds, const Gemm g, const Sched& S, const Epi& E) {
;     ...
;             PG8_WAIT_V(8); PG8_WAIT_L(0); PG8_BAR; PG8_MMA(1, 0, At, B0); PG8_MMA(1, 1, At, B1); PG8_BAR; PG8_SCHED;
;             } else {
;             PG8_LDB(B0, 0, 0); PG8_SCHED; PG8_LDA(At, 0, 0); PG8_STAGE(PG8_SA(1, 1), a1 + hstep, voffA);
;             PG8_WAIT_L(8); PG8_BAR; PG8_WAIT_L(0); PG8_MMA(0, 0, At, B0); PG8_BAR; PG8_SCHED;
;             PG8_LDB(B1, 0, 1); PG8_STAGE(PG8_SB(0, 0), b2, voffB);
;             PG8_BAR; PG8_WAIT_L(0); PG8_MMA(0, 1, At, B1); PG8_BAR;
;             PG8_LDA(At, 0, 1); PG8_STAGE(PG8_SA(0, 0), a2, voffA);
;             PG8_BAR; PG8_WAIT_L(0); PG8_MMA(1, 0, At, B0); PG8_BAR; PG8_SCHED;
;             PG8_STAGE(PG8_SB(0, 1), b2 + hstep, voffB);
;             PG8_WAIT_V(6); PG8_BAR; PG8_MMA(1, 1, At, B1); PG8_BAR;
;             PG8_LDB(B0, 1, 0); PG8_SCHED; PG8_LDA(At, 1, 0); PG8_STAGE(PG8_SA(0, 1), a2 + hstep, voffA);
;             PG8_WAIT_L(8); PG8_BAR; PG8_WAIT_L(0); PG8_MMA(0, 0, At, B0); PG8_BAR; PG8_SCHED;
;             PG8_LDB(B1, 1, 1); PG8_STAGE(PG8_SB(1, 0), b3, voffB);
;             PG8_BAR; PG8_WAIT_L(0); PG8_MMA(0, 1, At, B1); PG8_BAR;
	s_setprio 1
	s_waitcnt lgkmcnt(0)
	v_mfma_f32_16x16x32_bf16 v[60:63], v[144:147], v[176:179], v[60:63]
	v_mfma_f32_16x16x32_bf16 v[52:55], v[152:155], v[176:179], v[52:55]
	v_mfma_f32_16x16x32_bf16 v[44:47], v[144:147], v[194:197], v[44:47]
	v_mfma_f32_16x16x32_bf16 v[36:39], v[152:155], v[194:197], v[36:39]
	v_mfma_f32_16x16x32_bf16 v[28:31], v[144:147], v[202:205], v[28:31]
	v_mfma_f32_16x16x32_bf16 v[20:23], v[152:155], v[202:205], v[20:23]
	v_mfma_f32_16x16x32_bf16 v[12:15], v[144:147], v[210:213], v[12:15]
	v_mfma_f32_16x16x32_bf16 v[4:7], v[152:155], v[210:213], v[4:7]
	v_mfma_f32_16x16x32_bf16 v[60:63], v[148:151], v[180:183], v[60:63]
	v_mfma_f32_16x16x32_bf16 v[52:55], v[156:159], v[180:183], v[52:55]
	v_mfma_f32_16x16x32_bf16 v[44:47], v[148:151], v[198:201], v[44:47]
	v_mfma_f32_16x16x32_bf16 v[36:39], v[156:159], v[198:201], v[36:39]
	v_mfma_f32_16x16x32_bf16 v[28:31], v[148:151], v[206:209], v[28:31]
	v_mfma_f32_16x16x32_bf16 v[20:23], v[156:159], v[206:209], v[20:23]
	v_mfma_f32_16x16x32_bf16 v[12:15], v[148:151], v[228:231], v[12:15]
	v_mfma_f32_16x16x32_bf16 v[4:7], v[156:159], v[228:231], v[4:7]
	s_setprio 0
	s_setprio 1
	v_mfma_f32_16x16x32_bf16 v[56:59], v[160:163], v[176:179], v[56:59]
	v_mfma_f32_16x16x32_bf16 v[48:51], v[168:171], v[176:179], v[48:51]
	v_mfma_f32_16x16x32_bf16 v[40:43], v[160:163], v[194:197], v[40:43]
	v_mfma_f32_16x16x32_bf16 v[32:35], v[168:171], v[194:197], v[32:35]
	v_mfma_f32_16x16x32_bf16 v[24:27], v[160:163], v[202:205], v[24:27]
	v_mfma_f32_16x16x32_bf16 v[16:19], v[168:171], v[202:205], v[16:19]
	v_mfma_f32_16x16x32_bf16 v[8:11], v[160:163], v[210:213], v[8:11]
	v_mfma_f32_16x16x32_bf16 v[0:3], v[168:171], v[210:213], v[0:3]
	v_mfma_f32_16x16x32_bf16 v[56:59], v[164:167], v[180:183], v[56:59]
	v_mfma_f32_16x16x32_bf16 v[48:51], v[172:175], v[180:183], v[48:51]
	v_mfma_f32_16x16x32_bf16 v[40:43], v[164:167], v[198:201], v[40:43]
	v_mfma_f32_16x16x32_bf16 v[32:35], v[172:175], v[198:201], v[32:35]
	v_mfma_f32_16x16x32_bf16 v[24:27], v[164:167], v[206:209], v[24:27]
	v_mfma_f32_16x16x32_bf16 v[16:19], v[172:175], v[206:209], v[16:19]
	v_mfma_f32_16x16x32_bf16 v[8:11], v[164:167], v[228:231], v[8:11]
	v_mfma_f32_16x16x32_bf16 v[0:3], v[172:175], v[228:231], v[0:3]
	s_setprio 0
	s_barrier
	s_add_i32 s51, s51, 2
	s_add_u32 s0, s0, 0x100
	s_addc_u32 s1, s1, 0
	s_add_u32 s49, s49, 0x100
	s_addc_u32 s50, s50, 0
	s_cmp_gt_u32 s51, 13
	s_cbranch_scc0 .LBB0_35
	ds_read_b32 v146, v142
	s_and_b64 vcc, exec, s[12:13]
	s_cbranch_vccz .LBB0_38
	s_barrier
.LBB0_38:
	s_lshl_b32 s3, s48, 8
	v_mov_b32_e32 v145, 0xbfb8aa3b
	s_waitcnt lgkmcnt(0)
	v_pk_mul_f32 v[124:125], v[124:125], v[146:147] op_sel_hi:[1,0]
	v_pk_mul_f32 v[126:127], v[126:127], v[146:147] op_sel_hi:[1,0]
	v_pk_mul_f32 v[116:117], v[116:117], v[146:147] op_sel_hi:[1,0]
	v_pk_mul_f32 v[118:119], v[118:119], v[146:147] op_sel_hi:[1,0]
	v_pk_mul_f32 v[120:121], v[120:121], v[146:147] op_sel_hi:[1,0]
	v_pk_mul_f32 v[122:123], v[122:123], v[146:147] op_sel_hi:[1,0]
	v_pk_mul_f32 v[112:113], v[112:113], v[146:147] op_sel_hi:[1,0]
	v_pk_mul_f32 v[114:115], v[114:115], v[146:147] op_sel_hi:[1,0]
	v_pk_mul_f32 v[148:149], v[124:125], v[144:145] op_sel:[0,1] op_sel_hi:[1,1]
	v_exp_f32_e32 v148, v148
	v_exp_f32_e32 v149, v149
	v_add_f32_e32 v148, 1.0, v148
	v_add_f32_e32 v149, 1.0, v149
	v_rcp_f32_e32 v148, v148
	v_rcp_f32_e32 v149, v149
	s_nop 0
	v_pk_mul_f32 v[124:125], v[124:125], v[148:149]
	v_pk_mul_f32 v[120:121], v[120:121], v[124:125]
	v_pk_mul_f32 v[148:149], v[126:127], v[144:145] op_sel:[0,1] op_sel_hi:[1,1]
	v_exp_f32_e32 v148, v148
	v_exp_f32_e32 v149, v149
	v_add_f32_e32 v148, 1.0, v148
	v_add_f32_e32 v149, 1.0, v149
	v_rcp_f32_e32 v148, v148
	v_rcp_f32_e32 v149, v149
	s_nop 0
	v_pk_mul_f32 v[126:127], v[126:127], v[148:149]
	v_pk_mul_f32 v[122:123], v[122:123], v[126:127]
	v_pk_mul_f32 v[148:149], v[116:117], v[144:145] op_sel:[0,1] op_sel_hi:[1,1]
	v_exp_f32_e32 v148, v148
	v_exp_f32_e32 v149, v149
	v_add_f32_e32 v148, 1.0, v148
	v_add_f32_e32 v149, 1.0, v149
	v_rcp_f32_e32 v148, v148
	v_rcp_f32_e32 v149, v149
	s_nop 0
	v_pk_mul_f32 v[116:117], v[116:117], v[148:149]
	v_pk_mul_f32 v[112:113], v[112:113], v[116:117]
	v_pk_mul_f32 v[148:149], v[118:119], v[144:145] op_sel:[0,1] op_sel_hi:[1,1]
	v_exp_f32_e32 v148, v148
	v_exp_f32_e32 v149, v149
	v_add_f32_e32 v148, 1.0, v148
	v_add_f32_e32 v149, 1.0, v149
	v_rcp_f32_e32 v148, v148
	v_rcp_f32_e32 v149, v149
	s_nop 0
	v_pk_mul_f32 v[118:119], v[118:119], v[148:149]
	v_pk_mul_f32 v[114:115], v[114:115], v[118:119]
	v_cvt_pk_bf16_f32 v116, v112, v113
	v_cvt_pk_bf16_f32 v117, v114, v115
	v_cvt_pk_bf16_f32 v114, v120, v121
	v_cvt_pk_bf16_f32 v115, v122, v123
	s_lshl_b32 s0, s47, 7
	v_add_u32_e32 v144, s3, v140
	s_ashr_i32 s1, s0, 31
	s_movk_i32 s3, 0x1600
	s_lshl_b64 s[0:1], s[0:1], 1
	s_andn2_b64 vcc, exec, s[36:37]
	v_mov_b64_e32 v[112:113], s[16:17]
	s_mov_b32 s101, 0
	v_mad_i64_i32 v[118:119], s[4:5], v144, s3, v[112:113]
	v_lshl_add_u64 v[118:119], v[118:119], 0, s[0:1]
	v_lshl_add_u64 v[118:119], v[118:119], 0, s[34:35]
	v_lshl_add_u64 v[118:119], v[118:119], 0, v[184:185]
	global_store_dwordx4 v[118:119], v[114:117], off
	ds_read_b32 v114, v142 offset:64
	ds_read_b32 v120, v142 offset:128
	ds_read_b32 v122, v142 offset:192
	ds_read_b32 v124, v142 offset:512
	ds_read_b32 v126, v142 offset:576
	ds_read_b32 v112, v142 offset:640
	ds_read_b32 v116, v142 offset:704
	v_mov_b32_e32 v146, 1.0
	s_waitcnt lgkmcnt(6)
; __device__ __forceinline__ u32x4 pack8(const f32x4 a, const f32x4 b) { u32x4 w; w.x = cvt_pk_bf16(a[0], a[1]); w.y = cvt_pk_bf16(a[2], a[3]); w.z = cvt_pk_bf16(b[0], b[1]); w.w = cvt_pk_bf16(b[2], b[3]); return w; }
;     __device__ __forceinline__ void operator()(const f32x4 (&acc)[2][2][4][2], const Unit& u, int wr, int wc, int fr, int fq) const {
;     ...
;             for (int m = 0; m < 4; ++m) {
;                 const int row = u.pm * BM + ai * HALF + wr * 64 + m * 16 + fr;
;                 const float rs = R[ai * HALF + wr * 64 + m * 16 + fr];
;                 bf16_t* ACT = (bf16_t*)(ws + WS_ACT);
;                 f32x4 a[2];
; #pragma unroll
;                 for (int n = 0; n < 2; ++n) {
;                     const f32x4 g = acc[ai][0][m][n] * rs, uu = acc[ai][1][m][n] * rs;
; #pragma unroll
;                     for (int j = 0; j < 4; ++j) a[n][j] = g[j] * __builtin_amdgcn_rcpf(1.0f + __builtin_amdgcn_exp2f(-1.4426950408889634f * g[j])) * uu[j];
;                 }
;                 *(u32x4*)(ACT + (size_t)row * 2816 + u.pn * 128 + wc * 32 + 8 * fq) = pack8(a[0], a[1]);
;             }
	v_pk_mul_f32 v[108:109], v[108:109], v[114:115] op_sel_hi:[1,0]
	v_pk_mul_f32 v[110:111], v[110:111], v[114:115] op_sel_hi:[1,0]
	v_pk_mul_f32 v[100:101], v[100:101], v[114:115] op_sel_hi:[1,0]
	v_pk_mul_f32 v[102:103], v[102:103], v[114:115] op_sel_hi:[1,0]
	v_pk_mul_f32 v[104:105], v[104:105], v[114:115] op_sel_hi:[1,0]
	v_pk_mul_f32 v[106:107], v[106:107], v[114:115] op_sel_hi:[1,0]
	v_pk_mul_f32 v[96:97], v[96:97], v[114:115] op_sel_hi:[1,0]
	v_pk_mul_f32 v[98:99], v[98:99], v[114:115] op_sel_hi:[1,0]
	v_pk_mul_f32 v[148:149], v[108:109], v[144:145] op_sel:[0,1] op_sel_hi:[1,1]
	v_exp_f32_e32 v148, v148
	v_exp_f32_e32 v149, v149
	v_add_f32_e32 v148, 1.0, v148
	v_add_f32_e32 v149, 1.0, v149
	v_rcp_f32_e32 v148, v148
	v_rcp_f32_e32 v149, v149
	s_nop 0
	v_pk_mul_f32 v[108:109], v[108:109], v[148:149]
	v_pk_mul_f32 v[104:105], v[104:105], v[108:109]
	v_pk_mul_f32 v[148:149], v[110:111], v[144:145] op_sel:[0,1] op_sel_hi:[1,1]
	v_exp_f32_e32 v148, v148
	v_exp_f32_e32 v149, v149
	v_add_f32_e32 v148, 1.0, v148
	v_add_f32_e32 v149, 1.0, v149
	v_rcp_f32_e32 v148, v148
	v_rcp_f32_e32 v149, v149
	s_nop 0
	v_pk_mul_f32 v[110:111], v[110:111], v[148:149]
	v_pk_mul_f32 v[106:107], v[106:107], v[110:111]
	v_pk_mul_f32 v[148:149], v[100:101], v[144:145] op_sel:[0,1] op_sel_hi:[1,1]
	v_exp_f32_e32 v148, v148
	v_exp_f32_e32 v149, v149
	v_add_f32_e32 v148, 1.0, v148
	v_add_f32_e32 v149, 1.0, v149
	v_rcp_f32_e32 v148, v148
	v_rcp_f32_e32 v149, v149
	s_nop 0
	v_pk_mul_f32 v[100:101], v[100:101], v[148:149]
	v_pk_mul_f32 v[96:97], v[96:97], v[100:101]
	v_pk_mul_f32 v[148:149], v[102:103], v[144:145] op_sel:[0,1] op_sel_hi:[1,1]
	v_exp_f32_e32 v148, v148
	v_exp_f32_e32 v149, v149
	v_add_f32_e32 v148, 1.0, v148
	v_add_f32_e32 v149, 1.0, v149
	v_rcp_f32_e32 v148, v148
	v_rcp_f32_e32 v149, v149
	s_nop 0
	v_pk_mul_f32 v[102:103], v[102:103], v[148:149]
	v_pk_mul_f32 v[98:99], v[98:99], v[102:103]
	v_cvt_pk_bf16_f32 v99, v98, v99
	v_cvt_pk_bf16_f32 v98, v96, v97
	v_cvt_pk_bf16_f32 v96, v104, v105
	v_cvt_pk_bf16_f32 v97, v106, v107
	s_mov_b32 s100, 0x16000
	v_lshl_add_u64 v[100:101], v[118:119], 0, s[100:101]
	global_store_dwordx4 v[100:101], v[96:99], off
	s_waitcnt lgkmcnt(0)
	v_pk_mul_f32 v[92:93], v[92:93], v[120:121] op_sel_hi:[1,0]
	v_pk_mul_f32 v[94:95], v[94:95], v[120:121] op_sel_hi:[1,0]
	v_pk_mul_f32 v[84:85], v[84:85], v[120:121] op_sel_hi:[1,0]
	v_pk_mul_f32 v[86:87], v[86:87], v[120:121] op_sel_hi:[1,0]
	v_pk_mul_f32 v[88:89], v[88:89], v[120:121] op_sel_hi:[1,0]
	v_pk_mul_f32 v[90:91], v[90:91], v[120:121] op_sel_hi:[1,0]
	v_pk_mul_f32 v[80:81], v[80:81], v[120:121] op_sel_hi:[1,0]
	v_pk_mul_f32 v[82:83], v[82:83], v[120:121] op_sel_hi:[1,0]
	v_pk_mul_f32 v[148:149], v[92:93], v[144:145] op_sel:[0,1] op_sel_hi:[1,1]
	v_pk_mul_f32 v[114:115], v[94:95], v[144:145] op_sel:[0,1] op_sel_hi:[1,1]
	v_exp_f32_e32 v148, v148
	v_exp_f32_e32 v149, v149
	v_exp_f32_e32 v114, v114
	v_exp_f32_e32 v115, v115
	v_pk_add_f32 v[148:149], v[148:149], v[146:147] op_sel_hi:[1,0]
	v_pk_add_f32 v[114:115], v[114:115], v[146:147] op_sel_hi:[1,0]
	v_rcp_f32_e32 v148, v148
	v_rcp_f32_e32 v149, v149
	v_rcp_f32_e32 v114, v114
	v_rcp_f32_e32 v115, v115
	v_pk_mul_f32 v[92:93], v[92:93], v[148:149]
	v_pk_mul_f32 v[94:95], v[94:95], v[114:115]
	v_pk_mul_f32 v[88:89], v[88:89], v[92:93]
	v_pk_mul_f32 v[90:91], v[90:91], v[94:95]
	v_pk_mul_f32 v[148:149], v[84:85], v[144:145] op_sel:[0,1] op_sel_hi:[1,1]
	v_pk_mul_f32 v[114:115], v[86:87], v[144:145] op_sel:[0,1] op_sel_hi:[1,1]
	v_exp_f32_e32 v148, v148
	v_exp_f32_e32 v149, v149
	v_exp_f32_e32 v114, v114
	v_exp_f32_e32 v115, v115
	v_pk_add_f32 v[148:149], v[148:149], v[146:147] op_sel_hi:[1,0]
	v_pk_add_f32 v[114:115], v[114:115], v[146:147] op_sel_hi:[1,0]
	v_rcp_f32_e32 v148, v148
	v_rcp_f32_e32 v149, v149
	v_rcp_f32_e32 v114, v114
	v_rcp_f32_e32 v115, v115
	v_pk_mul_f32 v[84:85], v[84:85], v[148:149]
	v_pk_mul_f32 v[86:87], v[86:87], v[114:115]
	v_pk_mul_f32 v[80:81], v[80:81], v[84:85]
	v_pk_mul_f32 v[82:83], v[82:83], v[86:87]
	v_cvt_pk_bf16_f32 v83, v82, v83
	v_cvt_pk_bf16_f32 v82, v80, v81
	v_cvt_pk_bf16_f32 v80, v88, v89
	v_cvt_pk_bf16_f32 v81, v90, v91
	s_mov_b32 s100, 0x2c000
	v_lshl_add_u64 v[84:85], v[118:119], 0, s[100:101]
	global_store_dwordx4 v[84:85], v[80:83], off
	s_waitcnt lgkmcnt(0)
	v_pk_mul_f32 v[76:77], v[76:77], v[122:123] op_sel_hi:[1,0]
	v_pk_mul_f32 v[78:79], v[78:79], v[122:123] op_sel_hi:[1,0]
	v_pk_mul_f32 v[68:69], v[68:69], v[122:123] op_sel_hi:[1,0]
	v_pk_mul_f32 v[70:71], v[70:71], v[122:123] op_sel_hi:[1,0]
	v_pk_mul_f32 v[72:73], v[72:73], v[122:123] op_sel_hi:[1,0]
	v_pk_mul_f32 v[74:75], v[74:75], v[122:123] op_sel_hi:[1,0]
	v_pk_mul_f32 v[64:65], v[64:65], v[122:123] op_sel_hi:[1,0]
	v_pk_mul_f32 v[66:67], v[66:67], v[122:123] op_sel_hi:[1,0]
	v_pk_mul_f32 v[148:149], v[76:77], v[144:145] op_sel:[0,1] op_sel_hi:[1,1]
	v_pk_mul_f32 v[114:115], v[78:79], v[144:145] op_sel:[0,1] op_sel_hi:[1,1]
	v_exp_f32_e32 v148, v148
	v_exp_f32_e32 v149, v149
	v_exp_f32_e32 v114, v114
	v_exp_f32_e32 v115, v115
	v_pk_add_f32 v[148:149], v[148:149], v[146:147] op_sel_hi:[1,0]
	v_pk_add_f32 v[114:115], v[114:115], v[146:147] op_sel_hi:[1,0]
	v_rcp_f32_e32 v148, v148
	v_rcp_f32_e32 v149, v149
	v_rcp_f32_e32 v114, v114
	v_rcp_f32_e32 v115, v115
	v_pk_mul_f32 v[76:77], v[76:77], v[148:149]
	v_pk_mul_f32 v[78:79], v[78:79], v[114:115]
	v_pk_mul_f32 v[72:73], v[72:73], v[76:77]
	v_pk_mul_f32 v[74:75], v[74:75], v[78:79]
	v_pk_mul_f32 v[148:149], v[68:69], v[144:145] op_sel:[0,1] op_sel_hi:[1,1]
	v_pk_mul_f32 v[114:115], v[70:71], v[144:145] op_sel:[0,1] op_sel_hi:[1,1]
	v_exp_f32_e32 v148, v148
	v_exp_f32_e32 v149, v149
	v_exp_f32_e32 v114, v114
	v_exp_f32_e32 v115, v115
	v_pk_add_f32 v[148:149], v[148:149], v[146:147] op_sel_hi:[1,0]
	v_pk_add_f32 v[114:115], v[114:115], v[146:147] op_sel_hi:[1,0]
	v_rcp_f32_e32 v148, v148
	v_rcp_f32_e32 v149, v149
	v_rcp_f32_e32 v114, v114
	v_rcp_f32_e32 v115, v115
	v_pk_mul_f32 v[68:69], v[68:69], v[148:149]
	v_pk_mul_f32 v[70:71], v[70:71], v[114:115]
	v_pk_mul_f32 v[64:65], v[64:65], v[68:69]
	v_pk_mul_f32 v[66:67], v[66:67], v[70:71]
	v_cvt_pk_bf16_f32 v67, v66, v67
	v_cvt_pk_bf16_f32 v66, v64, v65
	v_cvt_pk_bf16_f32 v64, v72, v73
	v_cvt_pk_bf16_f32 v65, v74, v75
	s_mov_b32 s100, 0x42000
	v_lshl_add_u64 v[68:69], v[118:119], 0, s[100:101]
	global_store_dwordx4 v[68:69], v[64:67], off
	s_waitcnt lgkmcnt(0)
; __device__ __forceinline__ u32x4 pack8(const f32x4 a, const f32x4 b) { u32x4 w; w.x = cvt_pk_bf16(a[0], a[1]); w.y = cvt_pk_bf16(a[2], a[3]); w.z = cvt_pk_bf16(b[0], b[1]); w.w = cvt_pk_bf16(b[2], b[3]); return w; }
;     __device__ __forceinline__ void operator()(const f32x4 (&acc)[2][2][4][2], const Unit& u, int wr, int wc, int fr, int fq) const {
;     ...
;             for (int m = 0; m < 4; ++m) {
;                 const int row = u.pm * BM + ai * HALF + wr * 64 + m * 16 + fr;
;                 const float rs = R[ai * HALF + wr * 64 + m * 16 + fr];
;                 bf16_t* ACT = (bf16_t*)(ws + WS_ACT);
;                 f32x4 a[2];
; #pragma unroll
;                 for (int n = 0; n < 2; ++n) {
;                     const f32x4 g = acc[ai][0][m][n] * rs, uu = acc[ai][1][m][n] * rs;
; #pragma unroll
;                     for (int j = 0; j < 4; ++j) a[n][j] = g[j] * __builtin_amdgcn_rcpf(1.0f + __builtin_amdgcn_exp2f(-1.4426950408889634f * g[j])) * uu[j];
;                 }
;                 *(u32x4*)(ACT + (size_t)row * 2816 + u.pn * 128 + wc * 32 + 8 * fq) = pack8(a[0], a[1]);
;             }
	v_pk_mul_f32 v[60:61], v[60:61], v[124:125] op_sel_hi:[1,0]
	v_pk_mul_f32 v[62:63], v[62:63], v[124:125] op_sel_hi:[1,0]
	v_pk_mul_f32 v[52:53], v[52:53], v[124:125] op_sel_hi:[1,0]
	v_pk_mul_f32 v[54:55], v[54:55], v[124:125] op_sel_hi:[1,0]
	v_pk_mul_f32 v[56:57], v[56:57], v[124:125] op_sel_hi:[1,0]
	v_pk_mul_f32 v[58:59], v[58:59], v[124:125] op_sel_hi:[1,0]
	v_pk_mul_f32 v[48:49], v[48:49], v[124:125] op_sel_hi:[1,0]
	v_pk_mul_f32 v[50:51], v[50:51], v[124:125] op_sel_hi:[1,0]
	v_pk_mul_f32 v[148:149], v[60:61], v[144:145] op_sel:[0,1] op_sel_hi:[1,1]
	v_pk_mul_f32 v[114:115], v[62:63], v[144:145] op_sel:[0,1] op_sel_hi:[1,1]
	v_exp_f32_e32 v148, v148
	v_exp_f32_e32 v149, v149
	v_exp_f32_e32 v114, v114
	v_exp_f32_e32 v115, v115
	v_pk_add_f32 v[148:149], v[148:149], v[146:147] op_sel_hi:[1,0]
	v_pk_add_f32 v[114:115], v[114:115], v[146:147] op_sel_hi:[1,0]
	v_rcp_f32_e32 v148, v148
	v_rcp_f32_e32 v149, v149
	v_rcp_f32_e32 v114, v114
	v_rcp_f32_e32 v115, v115
	v_pk_mul_f32 v[60:61], v[60:61], v[148:149]
	v_pk_mul_f32 v[62:63], v[62:63], v[114:115]
	v_pk_mul_f32 v[56:57], v[56:57], v[60:61]
	v_pk_mul_f32 v[58:59], v[58:59], v[62:63]
	v_pk_mul_f32 v[148:149], v[52:53], v[144:145] op_sel:[0,1] op_sel_hi:[1,1]
	v_pk_mul_f32 v[114:115], v[54:55], v[144:145] op_sel:[0,1] op_sel_hi:[1,1]
	v_exp_f32_e32 v148, v148
	v_exp_f32_e32 v149, v149
	v_exp_f32_e32 v114, v114
	v_exp_f32_e32 v115, v115
	v_pk_add_f32 v[148:149], v[148:149], v[146:147] op_sel_hi:[1,0]
	v_pk_add_f32 v[114:115], v[114:115], v[146:147] op_sel_hi:[1,0]
	v_rcp_f32_e32 v148, v148
	v_rcp_f32_e32 v149, v149
	v_rcp_f32_e32 v114, v114
	v_rcp_f32_e32 v115, v115
	v_pk_mul_f32 v[52:53], v[52:53], v[148:149]
	v_pk_mul_f32 v[54:55], v[54:55], v[114:115]
	v_pk_mul_f32 v[48:49], v[48:49], v[52:53]
	v_pk_mul_f32 v[50:51], v[50:51], v[54:55]
	v_cvt_pk_bf16_f32 v51, v50, v51
	v_cvt_pk_bf16_f32 v50, v48, v49
	v_cvt_pk_bf16_f32 v48, v56, v57
	v_cvt_pk_bf16_f32 v49, v58, v59
	s_mov_b32 s100, 0xb0000
	v_lshl_add_u64 v[52:53], v[118:119], 0, s[100:101]
	global_store_dwordx4 v[52:53], v[48:51], off
	s_waitcnt lgkmcnt(0)
	v_pk_mul_f32 v[44:45], v[44:45], v[126:127] op_sel_hi:[1,0]
	v_pk_mul_f32 v[46:47], v[46:47], v[126:127] op_sel_hi:[1,0]
	v_pk_mul_f32 v[36:37], v[36:37], v[126:127] op_sel_hi:[1,0]
	v_pk_mul_f32 v[38:39], v[38:39], v[126:127] op_sel_hi:[1,0]
	v_pk_mul_f32 v[40:41], v[40:41], v[126:127] op_sel_hi:[1,0]
	v_pk_mul_f32 v[42:43], v[42:43], v[126:127] op_sel_hi:[1,0]
	v_pk_mul_f32 v[32:33], v[32:33], v[126:127] op_sel_hi:[1,0]
	v_pk_mul_f32 v[34:35], v[34:35], v[126:127] op_sel_hi:[1,0]
	v_pk_mul_f32 v[148:149], v[44:45], v[144:145] op_sel:[0,1] op_sel_hi:[1,1]
	v_pk_mul_f32 v[114:115], v[46:47], v[144:145] op_sel:[0,1] op_sel_hi:[1,1]
	v_exp_f32_e32 v148, v148
	v_exp_f32_e32 v149, v149
	v_exp_f32_e32 v114, v114
	v_exp_f32_e32 v115, v115
	v_pk_add_f32 v[148:149], v[148:149], v[146:147] op_sel_hi:[1,0]
	v_pk_add_f32 v[114:115], v[114:115], v[146:147] op_sel_hi:[1,0]
	v_rcp_f32_e32 v148, v148
	v_rcp_f32_e32 v149, v149
	v_rcp_f32_e32 v114, v114
	v_rcp_f32_e32 v115, v115
	v_pk_mul_f32 v[44:45], v[44:45], v[148:149]
	v_pk_mul_f32 v[46:47], v[46:47], v[114:115]
	v_pk_mul_f32 v[40:41], v[40:41], v[44:45]
	v_pk_mul_f32 v[42:43], v[42:43], v[46:47]
	v_pk_mul_f32 v[148:149], v[36:37], v[144:145] op_sel:[0,1] op_sel_hi:[1,1]
	v_pk_mul_f32 v[114:115], v[38:39], v[144:145] op_sel:[0,1] op_sel_hi:[1,1]
	v_exp_f32_e32 v148, v148
	v_exp_f32_e32 v149, v149
	v_exp_f32_e32 v114, v114
	v_exp_f32_e32 v115, v115
	v_pk_add_f32 v[148:149], v[148:149], v[146:147] op_sel_hi:[1,0]
	v_pk_add_f32 v[114:115], v[114:115], v[146:147] op_sel_hi:[1,0]
	v_rcp_f32_e32 v148, v148
	v_rcp_f32_e32 v149, v149
	v_rcp_f32_e32 v114, v114
	v_rcp_f32_e32 v115, v115
	v_pk_mul_f32 v[36:37], v[36:37], v[148:149]
	v_pk_mul_f32 v[38:39], v[38:39], v[114:115]
	v_pk_mul_f32 v[32:33], v[32:33], v[36:37]
	v_pk_mul_f32 v[34:35], v[34:35], v[38:39]
	v_cvt_pk_bf16_f32 v35, v34, v35
	v_cvt_pk_bf16_f32 v34, v32, v33
	v_cvt_pk_bf16_f32 v32, v40, v41
	v_cvt_pk_bf16_f32 v33, v42, v43
	s_mov_b32 s100, 0xc6000
	v_lshl_add_u64 v[36:37], v[118:119], 0, s[100:101]
	global_store_dwordx4 v[36:37], v[32:35], off
	s_waitcnt lgkmcnt(0)
; __device__ __forceinline__ u32x4 pack8(const f32x4 a, const f32x4 b) { u32x4 w; w.x = cvt_pk_bf16(a[0], a[1]); w.y = cvt_pk_bf16(a[2], a[3]); w.z = cvt_pk_bf16(b[0], b[1]); w.w = cvt_pk_bf16(b[2], b[3]); return w; }
;     __device__ __forceinline__ void operator()(const f32x4 (&acc)[2][2][4][2], const Unit& u, int wr, int wc, int fr, int fq) const {
;     ...
;             for (int m = 0; m < 4; ++m) {
;                 const int row = u.pm * BM + ai * HALF + wr * 64 + m * 16 + fr;
;                 const float rs = R[ai * HALF + wr * 64 + m * 16 + fr];
;                 bf16_t* ACT = (bf16_t*)(ws + WS_ACT);
;                 f32x4 a[2];
; #pragma unroll
;                 for (int n = 0; n < 2; ++n) {
;                     const f32x4 g = acc[ai][0][m][n] * rs, uu = acc[ai][1][m][n] * rs;
; #pragma unroll
;                     for (int j = 0; j < 4; ++j) a[n][j] = g[j] * __builtin_amdgcn_rcpf(1.0f + __builtin_amdgcn_exp2f(-1.4426950408889634f * g[j])) * uu[j];
;                 }
;                 *(u32x4*)(ACT + (size_t)row * 2816 + u.pn * 128 + wc * 32 + 8 * fq) = pack8(a[0], a[1]);
;             }
	v_pk_mul_f32 v[28:29], v[28:29], v[112:113] op_sel_hi:[1,0]
	v_pk_mul_f32 v[30:31], v[30:31], v[112:113] op_sel_hi:[1,0]
	v_pk_mul_f32 v[20:21], v[20:21], v[112:113] op_sel_hi:[1,0]
	v_pk_mul_f32 v[22:23], v[22:23], v[112:113] op_sel_hi:[1,0]
	v_pk_mul_f32 v[24:25], v[24:25], v[112:113] op_sel_hi:[1,0]
	v_pk_mul_f32 v[26:27], v[26:27], v[112:113] op_sel_hi:[1,0]
	v_pk_mul_f32 v[16:17], v[16:17], v[112:113] op_sel_hi:[1,0]
	v_pk_mul_f32 v[18:19], v[18:19], v[112:113] op_sel_hi:[1,0]
	v_pk_mul_f32 v[148:149], v[28:29], v[144:145] op_sel:[0,1] op_sel_hi:[1,1]
	v_pk_mul_f32 v[114:115], v[30:31], v[144:145] op_sel:[0,1] op_sel_hi:[1,1]
	v_exp_f32_e32 v148, v148
	v_exp_f32_e32 v149, v149
	v_exp_f32_e32 v114, v114
	v_exp_f32_e32 v115, v115
	v_pk_add_f32 v[148:149], v[148:149], v[146:147] op_sel_hi:[1,0]
	v_pk_add_f32 v[114:115], v[114:115], v[146:147] op_sel_hi:[1,0]
	v_rcp_f32_e32 v148, v148
	v_rcp_f32_e32 v149, v149
	v_rcp_f32_e32 v114, v114
	v_rcp_f32_e32 v115, v115
	v_pk_mul_f32 v[28:29], v[28:29], v[148:149]
	v_pk_mul_f32 v[30:31], v[30:31], v[114:115]
	v_pk_mul_f32 v[24:25], v[24:25], v[28:29]
	v_pk_mul_f32 v[26:27], v[26:27], v[30:31]
	v_pk_mul_f32 v[148:149], v[20:21], v[144:145] op_sel:[0,1] op_sel_hi:[1,1]
	v_pk_mul_f32 v[114:115], v[22:23], v[144:145] op_sel:[0,1] op_sel_hi:[1,1]
	v_exp_f32_e32 v148, v148
	v_exp_f32_e32 v149, v149
	v_exp_f32_e32 v114, v114
	v_exp_f32_e32 v115, v115
	v_pk_add_f32 v[148:149], v[148:149], v[146:147] op_sel_hi:[1,0]
	v_pk_add_f32 v[114:115], v[114:115], v[146:147] op_sel_hi:[1,0]
	v_rcp_f32_e32 v148, v148
	v_rcp_f32_e32 v149, v149
	v_rcp_f32_e32 v114, v114
	v_rcp_f32_e32 v115, v115
	v_pk_mul_f32 v[20:21], v[20:21], v[148:149]
	v_pk_mul_f32 v[22:23], v[22:23], v[114:115]
	v_pk_mul_f32 v[16:17], v[16:17], v[20:21]
	v_pk_mul_f32 v[18:19], v[18:19], v[22:23]
	v_cvt_pk_bf16_f32 v19, v18, v19
	v_cvt_pk_bf16_f32 v18, v16, v17
	v_cvt_pk_bf16_f32 v16, v24, v25
	v_cvt_pk_bf16_f32 v17, v26, v27
	s_mov_b32 s100, 0xdc000
	v_lshl_add_u64 v[20:21], v[118:119], 0, s[100:101]
	global_store_dwordx4 v[20:21], v[16:19], off
	s_waitcnt lgkmcnt(0)
	v_pk_mul_f32 v[12:13], v[12:13], v[116:117] op_sel_hi:[1,0]
	v_pk_mul_f32 v[14:15], v[14:15], v[116:117] op_sel_hi:[1,0]
	v_pk_mul_f32 v[4:5], v[4:5], v[116:117] op_sel_hi:[1,0]
	v_pk_mul_f32 v[6:7], v[6:7], v[116:117] op_sel_hi:[1,0]
	v_pk_mul_f32 v[8:9], v[8:9], v[116:117] op_sel_hi:[1,0]
	v_pk_mul_f32 v[10:11], v[10:11], v[116:117] op_sel_hi:[1,0]
	v_pk_mul_f32 v[0:1], v[0:1], v[116:117] op_sel_hi:[1,0]
	v_pk_mul_f32 v[2:3], v[2:3], v[116:117] op_sel_hi:[1,0]
	v_pk_mul_f32 v[148:149], v[12:13], v[144:145] op_sel:[0,1] op_sel_hi:[1,1]
	v_pk_mul_f32 v[114:115], v[14:15], v[144:145] op_sel:[0,1] op_sel_hi:[1,1]
	v_exp_f32_e32 v148, v148
	v_exp_f32_e32 v149, v149
	v_exp_f32_e32 v114, v114
	v_exp_f32_e32 v115, v115
	v_pk_add_f32 v[148:149], v[148:149], v[146:147] op_sel_hi:[1,0]
	v_pk_add_f32 v[114:115], v[114:115], v[146:147] op_sel_hi:[1,0]
	v_rcp_f32_e32 v148, v148
	v_rcp_f32_e32 v149, v149
	v_rcp_f32_e32 v114, v114
	v_rcp_f32_e32 v115, v115
	v_pk_mul_f32 v[12:13], v[12:13], v[148:149]
	v_pk_mul_f32 v[14:15], v[14:15], v[114:115]
	v_pk_mul_f32 v[8:9], v[8:9], v[12:13]
	v_pk_mul_f32 v[10:11], v[10:11], v[14:15]
	v_pk_mul_f32 v[148:149], v[4:5], v[144:145] op_sel:[0,1] op_sel_hi:[1,1]
	v_pk_mul_f32 v[114:115], v[6:7], v[144:145] op_sel:[0,1] op_sel_hi:[1,1]
	v_exp_f32_e32 v148, v148
	v_exp_f32_e32 v149, v149
	v_exp_f32_e32 v114, v114
	v_exp_f32_e32 v115, v115
	v_pk_add_f32 v[148:149], v[148:149], v[146:147] op_sel_hi:[1,0]
	v_pk_add_f32 v[114:115], v[114:115], v[146:147] op_sel_hi:[1,0]
	v_rcp_f32_e32 v148, v148
	v_rcp_f32_e32 v149, v149
	v_rcp_f32_e32 v114, v114
	v_rcp_f32_e32 v115, v115
	v_pk_mul_f32 v[4:5], v[4:5], v[148:149]
	v_pk_mul_f32 v[6:7], v[6:7], v[114:115]
	v_pk_mul_f32 v[0:1], v[0:1], v[4:5]
	v_pk_mul_f32 v[2:3], v[2:3], v[6:7]
	v_cvt_pk_bf16_f32 v3, v2, v3
	v_cvt_pk_bf16_f32 v2, v0, v1
	v_cvt_pk_bf16_f32 v0, v8, v9
	v_cvt_pk_bf16_f32 v1, v10, v11
	s_mov_b32 s100, 0xf2000
	v_lshl_add_u64 v[4:5], v[118:119], 0, s[100:101]
	s_mov_b64 s[0:1], -1
	global_store_dwordx4 v[4:5], v[0:3], off
	s_cbranch_vccnz .LBB0_31
	s_andn2_b64 vcc, exec, s[8:9]
	s_cbranch_vccnz .LBB0_30
	s_barrier
	s_branch .LBB0_30
